# phase +0 epilogue: specialized fast path for non-state tiles (bias+scale folded into one pk_fma, sigmoid exponent scale folded, no per-step phi copies or 64-bit address recomputation); state tiles kee
# speedup vs baseline: 1.0170x; 1.0009x over previous
; __device__ __forceinline__ unsigned pk2(float lo, float hi) { unsigned r; asm volatile("v_cvt_pk_bf16_f32 %0, %1, %2" : "=v"(r) : "v"(lo), "v"(hi)); return r; }
; __device__ __forceinline__ float sigmoid_fast(float x) { return __builtin_amdgcn_rcpf(1.0f + __expf(-x)); }
;     __device__ __forceinline__ void operator()(const f32x4 (&acc)[2][2][4][2], const Unit& u, int wr, int wc, int fr, int fq) const {
;     ...
;         const int cl = wc * 32 + 8 * fq;
;         const int bcol0 = pn * 256 + cl + (pn < 12 ? 0 : 8);
;         f32x4 bv[2][2];
; #pragma unroll
;         for (int bj = 0; bj < 2; ++bj)
; #pragma unroll
;             for (int n = 0; n < 2; ++n) bv[bj][n] = *(const f32x4*)(bias + bcol0 + bj * 128 + 4 * n);
; #pragma unroll
;         for (int ai = 0; ai < 2; ++ai)
; #pragma unroll
;             for (int m = 0; m < 4; ++m) {
;                 const int rloc = ai * 128 + wr * 64 + m * 16 + fr; const size_t row = (size_t)u.pm * 256 + rloc;
;                 bf16* rowp = base + row * ld + ct + cl;
;                 float* sp = nullptr;
;                 if (st) {
;                     if (u.pm >= 64) { const int rs = (u.pm - 64) * 256 + rloc; sp = so_s + ((size_t)(rs >> 2) * 128 + 124 + (rs & 3)) * 256 + cl; }
;                     else if ((u.pm & 7) == 7 && ai == 1) { sp = so_p + ((size_t)(u.pm >> 3) * 128 + (rloc - 128)) * 256 + cl; }
;                 }
; #pragma unroll
;                 for (int bj = 0; bj < 2; ++bj) {
;                     f32x4 v0 = (acc[ai][bj][m][0] + bv[bj][0]) * sc, v1 = (acc[ai][bj][m][1] + bv[bj][1]) * sc;
;                     if (act) {
; #pragma unroll
;                         for (int j = 0; j < 4; ++j) { v0[j] = sigmoid_fast(v0[j]); v1[j] = sigmoid_fast(v1[j]); }
;                     }
;                     u32x4 w; w.x = pk2(v0[0], v0[1]); w.y = pk2(v0[2], v0[3]); w.z = pk2(v1[0], v1[1]); w.w = pk2(v1[2], v1[3]);
;                     if (act) __builtin_nontemporal_store(w, (u32x4*)(rowp + bj * 128)); else *(u32x4*)(rowp + bj * 128) = w;
;                     if (sp) { *(f32x4*)(sp + bj * 128) = v0; *(f32x4*)(sp + bj * 128 + 4) = v1; }
;                 }
.LBB0_151:
	s_xor_b64 s[50:51], s[50:51], -1
	s_cmp_lt_i32 s8, 12
	s_cselect_b32 s11, 0, 8
	v_lshl_or_b32 v60, s8, 8, v174
	v_add_u32_e32 v60, s11, v60
	v_ashrrev_i32_e32 v61, 31, v60
	v_lshl_add_u64 v[68:69], v[60:61], 2, s[16:17]
	global_load_dwordx4 v[80:83], v[68:69], off
	global_load_dwordx4 v[76:79], v[68:69], off offset:16
	global_load_dwordx4 v[60:63], v[68:69], off offset:528
	s_nop 0
	global_load_dwordx4 v[68:71], v[68:69], off offset:512
	s_mov_b64 s[54:55], -1
	s_and_b64 vcc, exec, s[50:51]
	s_waitcnt vmcnt(0)
	s_cmp_eq_u64 s[40:41], -1
	s_cbranch_scc1 .Lepiin_fast
	v_pk_add_f32 v[142:143], v[142:143], v[82:83]
	v_pk_add_f32 v[140:141], v[140:141], v[80:81]
	v_pk_add_f32 v[146:147], v[146:147], v[78:79]
	v_pk_add_f32 v[144:145], v[144:145], v[76:77]
	v_pk_mul_f32 v[164:165], s[48:49], v[142:143] op_sel_hi:[0,1]
	v_pk_mul_f32 v[162:163], s[48:49], v[140:141] op_sel_hi:[0,1]
	v_pk_mul_f32 v[142:143], s[48:49], v[146:147] op_sel_hi:[0,1]
	v_pk_mul_f32 v[140:141], s[48:49], v[144:145] op_sel_hi:[0,1]
	s_cbranch_vccz .LBB0_153
	v_mul_f32_e32 v144, 0xbfb8aa3b, v162
	v_exp_f32_e32 v144, v144
	v_mul_f32_e32 v145, 0xbfb8aa3b, v140
	v_mul_f32_e32 v146, 0xbfb8aa3b, v163
	v_exp_f32_e32 v145, v145
	v_exp_f32_e32 v147, v146
	v_add_f32_e32 v144, 1.0, v144
	v_rcp_f32_e32 v150, v144
	v_add_f32_e32 v144, 1.0, v145
	v_mul_f32_e32 v145, 0xbfb8aa3b, v141
	v_rcp_f32_e32 v146, v144
	v_add_f32_e32 v144, 1.0, v147
	v_exp_f32_e32 v145, v145
	v_mul_f32_e32 v147, 0xbfb8aa3b, v164
	v_exp_f32_e32 v148, v147
	v_rcp_f32_e32 v151, v144
	v_add_f32_e32 v144, 1.0, v145
	v_rcp_f32_e32 v147, v144
	v_add_f32_e32 v144, 1.0, v148
	v_rcp_f32_e32 v152, v144
	v_mul_f32_e32 v144, 0xbfb8aa3b, v142
	v_exp_f32_e32 v144, v144
	v_mul_f32_e32 v145, 0xbfb8aa3b, v165
	v_mul_f32_e32 v148, 0xbfb8aa3b, v143
	v_exp_f32_e32 v145, v145
	v_exp_f32_e32 v149, v148
	v_add_f32_e32 v144, 1.0, v144
	v_rcp_f32_e32 v148, v144
	v_add_f32_e32 v144, 1.0, v145
	v_add_f32_e32 v145, 1.0, v149
	v_rcp_f32_e32 v149, v145
	v_rcp_f32_e32 v153, v144
	s_mov_b64 s[54:55], 0
	v_mov_b64_e32 v[156:157], v[148:149]
	v_mov_b64_e32 v[160:161], v[152:153]
	v_mov_b64_e32 v[154:155], v[146:147]
	v_mov_b64_e32 v[158:159], v[150:151]

; #define PG8_BAR __builtin_amdgcn_s_barrier()
; template <class Epi, class Sched>
; __device__ __forceinline__ void gemm_phase(const int tid, LAS unsigned char* lds, const bf16* Aop, const bf16* Bop, const int K_, const Sched& S, const Epi& E, const bf16* Aop1 = nullptr, const bf16* Bop1 = nullptr) {
;     ...
;         if (wr == 0) PG8_BAR;
;         E(acc, cur, wr, wc, fr, fq);
;         if (!has_next) break;
; #pragma unroll
;         for (int a = 0; a < 2; ++a)
; #pragma unroll
;             for (int b = 0; b < 2; ++b)
; #pragma unroll
;                 for (int m = 0; m < 4; ++m)
; #pragma unroll
;                     for (int n = 0; n < 2; ++n) acc[a][b][m][n] = (f32x4){0.f, 0.f, 0.f, 0.f};
;         cur = nxt; cA = nA; cB = nB; ++ui;
;         if (wr == 1) PG8_BAR;
.Lepiin_join:
	s_and_b64 vcc, exec, s[38:39]
	s_mov_b64 s[10:11], -1
	s_cbranch_vccnz .LBB0_118
	s_andn2_b64 vcc, exec, s[14:15]
	s_cbranch_vccnz .LBB0_117
	s_barrier
	s_branch .LBB0_117

; __device__ __forceinline__ unsigned pk2(float lo, float hi) { unsigned r; asm volatile("v_cvt_pk_bf16_f32 %0, %1, %2" : "=v"(r) : "v"(lo), "v"(hi)); return r; }
; __device__ __forceinline__ float sigmoid_fast(float x) { return __builtin_amdgcn_rcpf(1.0f + __expf(-x)); }
;     __device__ __forceinline__ void operator()(const f32x4 (&acc)[2][2][4][2], const Unit& u, int wr, int wc, int fr, int fq) const {
;     ...
;         const int cl = wc * 32 + 8 * fq;
;         const int bcol0 = pn * 256 + cl + (pn < 12 ? 0 : 8);
;         f32x4 bv[2][2];
; #pragma unroll
;         for (int bj = 0; bj < 2; ++bj)
; #pragma unroll
;             for (int n = 0; n < 2; ++n) bv[bj][n] = *(const f32x4*)(bias + bcol0 + bj * 128 + 4 * n);
; #pragma unroll
;         for (int ai = 0; ai < 2; ++ai)
; #pragma unroll
;             for (int m = 0; m < 4; ++m) {
;                 const int rloc = ai * 128 + wr * 64 + m * 16 + fr; const size_t row = (size_t)u.pm * 256 + rloc;
;                 bf16* rowp = base + row * ld + ct + cl;
;                 float* sp = nullptr;
;                 if (st) {
;                     if (u.pm >= 64) { const int rs = (u.pm - 64) * 256 + rloc; sp = so_s + ((size_t)(rs >> 2) * 128 + 124 + (rs & 3)) * 256 + cl; }
;                     else if ((u.pm & 7) == 7 && ai == 1) { sp = so_p + ((size_t)(u.pm >> 3) * 128 + (rloc - 128)) * 256 + cl; }
;                 }
; #pragma unroll
;                 for (int bj = 0; bj < 2; ++bj) {
;                     f32x4 v0 = (acc[ai][bj][m][0] + bv[bj][0]) * sc, v1 = (acc[ai][bj][m][1] + bv[bj][1]) * sc;
;                     if (act) {
; #pragma unroll
;                         for (int j = 0; j < 4; ++j) { v0[j] = sigmoid_fast(v0[j]); v1[j] = sigmoid_fast(v1[j]); }
;                     }
;                     u32x4 w; w.x = pk2(v0[0], v0[1]); w.y = pk2(v0[2], v0[3]); w.z = pk2(v1[0], v1[1]); w.w = pk2(v1[2], v1[3]);
;                     if (act) __builtin_nontemporal_store(w, (u32x4*)(rowp + bj * 128)); else *(u32x4*)(rowp + bj * 128) = w;
;                     if (sp) { *(f32x4*)(sp + bj * 128) = v0; *(f32x4*)(sp + bj * 128 + 4) = v1; }
;                 }
.Lepiin_fast:
	s_add_u32 s49, s46, s52
	s_addc_u32 s54, s47, s53
	s_ashr_i32 s11, s10, 31
	s_ashr_i32 s45, s44, 31
	s_lshl_b64 s[52:53], s[10:11], 8
	s_lshl_b64 s[44:45], s[44:45], 1
	s_add_u32 s44, s49, s44
	s_addc_u32 s45, s54, s45
	v_mov_b32_e32 v203, v2
	v_lshl_add_u64 v[148:149], s[52:53], 0, v[172:173]
	v_lshl_add_u64 v[162:163], s[44:45], 0, v[202:203]
	v_mul_lo_u32 v150, s27, v148
	v_mul_lo_u32 v151, s26, v149
	v_mad_u64_u32 v[148:149], s[56:57], s26, v148, 0
	v_add3_u32 v149, v149, v151, v150
	v_lshl_add_u64 v[206:207], v[148:149], 1, v[162:163]
	s_lshl_b32 s58, s26, 5
	s_lshl_b32 s59, s26, 8
	s_and_b64 vcc, exec, s[50:51]
	s_cbranch_vccz .Lepiin_noact
	s_mov_b32 s48, 0xbfb8aa3b
.Lepiin_noact:
	v_pk_mul_f32 v[80:81], v[80:81], s[48:49] op_sel_hi:[1,0]
	v_pk_mul_f32 v[82:83], v[82:83], s[48:49] op_sel_hi:[1,0]
	v_pk_mul_f32 v[76:77], v[76:77], s[48:49] op_sel_hi:[1,0]
	v_pk_mul_f32 v[78:79], v[78:79], s[48:49] op_sel_hi:[1,0]
	v_pk_mul_f32 v[68:69], v[68:69], s[48:49] op_sel_hi:[1,0]
	v_pk_mul_f32 v[70:71], v[70:71], s[48:49] op_sel_hi:[1,0]
	v_pk_mul_f32 v[60:61], v[60:61], s[48:49] op_sel_hi:[1,0]
	v_pk_mul_f32 v[62:63], v[62:63], s[48:49] op_sel_hi:[1,0]
	s_mov_b32 s44, 0
	s_mov_b32 s45, 0
	s_cbranch_vccnz .Lepiin_act
	v_pk_fma_f32 v[140:141], v[140:141], s[48:49], v[80:81] op_sel_hi:[1,0,1]
	v_pk_fma_f32 v[142:143], v[142:143], s[48:49], v[82:83] op_sel_hi:[1,0,1]
	v_pk_fma_f32 v[144:145], v[144:145], s[48:49], v[76:77] op_sel_hi:[1,0,1]
	v_pk_fma_f32 v[146:147], v[146:147], s[48:49], v[78:79] op_sel_hi:[1,0,1]
	v_cvt_pk_bf16_f32 v140, v140, v141
	v_cvt_pk_bf16_f32 v141, v142, v143
	v_cvt_pk_bf16_f32 v142, v144, v145
	v_cvt_pk_bf16_f32 v143, v146, v147
	global_store_dwordx4 v[206:207], v[140:143], off
	v_pk_fma_f32 v[136:137], v[136:137], s[48:49], v[68:69] op_sel_hi:[1,0,1]
	v_pk_fma_f32 v[138:139], v[138:139], s[48:49], v[70:71] op_sel_hi:[1,0,1]
	v_pk_fma_f32 v[132:133], v[132:133], s[48:49], v[60:61] op_sel_hi:[1,0,1]
	v_pk_fma_f32 v[134:135], v[134:135], s[48:49], v[62:63] op_sel_hi:[1,0,1]
	v_cvt_pk_bf16_f32 v136, v136, v137
	v_cvt_pk_bf16_f32 v137, v138, v139
	v_cvt_pk_bf16_f32 v138, v132, v133
	v_cvt_pk_bf16_f32 v139, v134, v135
	global_store_dwordx4 v[206:207], v[136:139], off offset:256
	s_add_u32 s44, s44, s58
	v_lshl_add_u64 v[208:209], v[206:207], 0, s[44:45]
	v_pk_fma_f32 v[128:129], v[128:129], s[48:49], v[80:81] op_sel_hi:[1,0,1]
	v_pk_fma_f32 v[130:131], v[130:131], s[48:49], v[82:83] op_sel_hi:[1,0,1]
	v_pk_fma_f32 v[124:125], v[124:125], s[48:49], v[76:77] op_sel_hi:[1,0,1]
	v_pk_fma_f32 v[126:127], v[126:127], s[48:49], v[78:79] op_sel_hi:[1,0,1]
	v_cvt_pk_bf16_f32 v128, v128, v129
	v_cvt_pk_bf16_f32 v129, v130, v131
	v_cvt_pk_bf16_f32 v130, v124, v125
	v_cvt_pk_bf16_f32 v131, v126, v127
	global_store_dwordx4 v[208:209], v[128:131], off
	v_pk_fma_f32 v[120:121], v[120:121], s[48:49], v[68:69] op_sel_hi:[1,0,1]
	v_pk_fma_f32 v[122:123], v[122:123], s[48:49], v[70:71] op_sel_hi:[1,0,1]
	v_pk_fma_f32 v[116:117], v[116:117], s[48:49], v[60:61] op_sel_hi:[1,0,1]
	v_pk_fma_f32 v[118:119], v[118:119], s[48:49], v[62:63] op_sel_hi:[1,0,1]
	v_cvt_pk_bf16_f32 v120, v120, v121
	v_cvt_pk_bf16_f32 v121, v122, v123
	v_cvt_pk_bf16_f32 v122, v116, v117
	v_cvt_pk_bf16_f32 v123, v118, v119
	global_store_dwordx4 v[208:209], v[120:123], off offset:256
	s_add_u32 s44, s44, s58
	v_lshl_add_u64 v[208:209], v[206:207], 0, s[44:45]
	v_pk_fma_f32 v[112:113], v[112:113], s[48:49], v[80:81] op_sel_hi:[1,0,1]
	v_pk_fma_f32 v[114:115], v[114:115], s[48:49], v[82:83] op_sel_hi:[1,0,1]
	v_pk_fma_f32 v[108:109], v[108:109], s[48:49], v[76:77] op_sel_hi:[1,0,1]
	v_pk_fma_f32 v[110:111], v[110:111], s[48:49], v[78:79] op_sel_hi:[1,0,1]
	v_cvt_pk_bf16_f32 v112, v112, v113
	v_cvt_pk_bf16_f32 v113, v114, v115
	v_cvt_pk_bf16_f32 v114, v108, v109
	v_cvt_pk_bf16_f32 v115, v110, v111
	global_store_dwordx4 v[208:209], v[112:115], off
	v_pk_fma_f32 v[104:105], v[104:105], s[48:49], v[68:69] op_sel_hi:[1,0,1]
	v_pk_fma_f32 v[106:107], v[106:107], s[48:49], v[70:71] op_sel_hi:[1,0,1]
	v_pk_fma_f32 v[100:101], v[100:101], s[48:49], v[60:61] op_sel_hi:[1,0,1]
	v_pk_fma_f32 v[102:103], v[102:103], s[48:49], v[62:63] op_sel_hi:[1,0,1]
	v_cvt_pk_bf16_f32 v104, v104, v105
	v_cvt_pk_bf16_f32 v105, v106, v107
	v_cvt_pk_bf16_f32 v106, v100, v101
	v_cvt_pk_bf16_f32 v107, v102, v103
	global_store_dwordx4 v[208:209], v[104:107], off offset:256
	s_add_u32 s44, s44, s58
	v_lshl_add_u64 v[208:209], v[206:207], 0, s[44:45]
	v_pk_fma_f32 v[96:97], v[96:97], s[48:49], v[80:81] op_sel_hi:[1,0,1]
	v_pk_fma_f32 v[98:99], v[98:99], s[48:49], v[82:83] op_sel_hi:[1,0,1]
	v_pk_fma_f32 v[92:93], v[92:93], s[48:49], v[76:77] op_sel_hi:[1,0,1]
	v_pk_fma_f32 v[94:95], v[94:95], s[48:49], v[78:79] op_sel_hi:[1,0,1]
	v_cvt_pk_bf16_f32 v96, v96, v97
	v_cvt_pk_bf16_f32 v97, v98, v99
	v_cvt_pk_bf16_f32 v98, v92, v93
	v_cvt_pk_bf16_f32 v99, v94, v95
	global_store_dwordx4 v[208:209], v[96:99], off
	v_pk_fma_f32 v[88:89], v[88:89], s[48:49], v[68:69] op_sel_hi:[1,0,1]
	v_pk_fma_f32 v[90:91], v[90:91], s[48:49], v[70:71] op_sel_hi:[1,0,1]
	v_pk_fma_f32 v[84:85], v[84:85], s[48:49], v[60:61] op_sel_hi:[1,0,1]
	v_pk_fma_f32 v[86:87], v[86:87], s[48:49], v[62:63] op_sel_hi:[1,0,1]
	v_cvt_pk_bf16_f32 v88, v88, v89
	v_cvt_pk_bf16_f32 v89, v90, v91
	v_cvt_pk_bf16_f32 v90, v84, v85
	v_cvt_pk_bf16_f32 v91, v86, v87
	global_store_dwordx4 v[208:209], v[88:91], off offset:256
	s_mov_b32 s44, s59
	v_lshl_add_u64 v[208:209], v[206:207], 0, s[44:45]
	v_pk_fma_f32 v[72:73], v[72:73], s[48:49], v[80:81] op_sel_hi:[1,0,1]
	v_pk_fma_f32 v[74:75], v[74:75], s[48:49], v[82:83] op_sel_hi:[1,0,1]
; __device__ __forceinline__ unsigned pk2(float lo, float hi) { unsigned r; asm volatile("v_cvt_pk_bf16_f32 %0, %1, %2" : "=v"(r) : "v"(lo), "v"(hi)); return r; }
; __device__ __forceinline__ float sigmoid_fast(float x) { return __builtin_amdgcn_rcpf(1.0f + __expf(-x)); }
;     __device__ __forceinline__ void operator()(const f32x4 (&acc)[2][2][4][2], const Unit& u, int wr, int wc, int fr, int fq) const {
;     ...
;         const int cl = wc * 32 + 8 * fq;
;         const int bcol0 = pn * 256 + cl + (pn < 12 ? 0 : 8);
;         f32x4 bv[2][2];
; #pragma unroll
;         for (int bj = 0; bj < 2; ++bj)
; #pragma unroll
;             for (int n = 0; n < 2; ++n) bv[bj][n] = *(const f32x4*)(bias + bcol0 + bj * 128 + 4 * n);
; #pragma unroll
;         for (int ai = 0; ai < 2; ++ai)
; #pragma unroll
;             for (int m = 0; m < 4; ++m) {
;                 const int rloc = ai * 128 + wr * 64 + m * 16 + fr; const size_t row = (size_t)u.pm * 256 + rloc;
;                 bf16* rowp = base + row * ld + ct + cl;
;                 float* sp = nullptr;
;                 if (st) {
;                     if (u.pm >= 64) { const int rs = (u.pm - 64) * 256 + rloc; sp = so_s + ((size_t)(rs >> 2) * 128 + 124 + (rs & 3)) * 256 + cl; }
;                     else if ((u.pm & 7) == 7 && ai == 1) { sp = so_p + ((size_t)(u.pm >> 3) * 128 + (rloc - 128)) * 256 + cl; }
;                 }
; #pragma unroll
;                 for (int bj = 0; bj < 2; ++bj) {
;                     f32x4 v0 = (acc[ai][bj][m][0] + bv[bj][0]) * sc, v1 = (acc[ai][bj][m][1] + bv[bj][1]) * sc;
;                     if (act) {
; #pragma unroll
;                         for (int j = 0; j < 4; ++j) { v0[j] = sigmoid_fast(v0[j]); v1[j] = sigmoid_fast(v1[j]); }
;                     }
;                     u32x4 w; w.x = pk2(v0[0], v0[1]); w.y = pk2(v0[2], v0[3]); w.z = pk2(v1[0], v1[1]); w.w = pk2(v1[2], v1[3]);
;                     if (act) __builtin_nontemporal_store(w, (u32x4*)(rowp + bj * 128)); else *(u32x4*)(rowp + bj * 128) = w;
;                     if (sp) { *(f32x4*)(sp + bj * 128) = v0; *(f32x4*)(sp + bj * 128 + 4) = v1; }
;                 }
	v_pk_fma_f32 v[64:65], v[64:65], s[48:49], v[76:77] op_sel_hi:[1,0,1]
	v_pk_fma_f32 v[66:67], v[66:67], s[48:49], v[78:79] op_sel_hi:[1,0,1]
	v_cvt_pk_bf16_f32 v72, v72, v73
	v_cvt_pk_bf16_f32 v73, v74, v75
	v_cvt_pk_bf16_f32 v74, v64, v65
	v_cvt_pk_bf16_f32 v75, v66, v67
	global_store_dwordx4 v[208:209], v[72:75], off
	v_pk_fma_f32 v[56:57], v[56:57], s[48:49], v[68:69] op_sel_hi:[1,0,1]
	v_pk_fma_f32 v[58:59], v[58:59], s[48:49], v[70:71] op_sel_hi:[1,0,1]
	v_pk_fma_f32 v[52:53], v[52:53], s[48:49], v[60:61] op_sel_hi:[1,0,1]
	v_pk_fma_f32 v[54:55], v[54:55], s[48:49], v[62:63] op_sel_hi:[1,0,1]
	v_cvt_pk_bf16_f32 v56, v56, v57
	v_cvt_pk_bf16_f32 v57, v58, v59
	v_cvt_pk_bf16_f32 v58, v52, v53
	v_cvt_pk_bf16_f32 v59, v54, v55
	global_store_dwordx4 v[208:209], v[56:59], off offset:256
	s_add_u32 s44, s44, s58
	v_lshl_add_u64 v[208:209], v[206:207], 0, s[44:45]
	v_pk_fma_f32 v[48:49], v[48:49], s[48:49], v[80:81] op_sel_hi:[1,0,1]
	v_pk_fma_f32 v[50:51], v[50:51], s[48:49], v[82:83] op_sel_hi:[1,0,1]
	v_pk_fma_f32 v[44:45], v[44:45], s[48:49], v[76:77] op_sel_hi:[1,0,1]
	v_pk_fma_f32 v[46:47], v[46:47], s[48:49], v[78:79] op_sel_hi:[1,0,1]
	v_cvt_pk_bf16_f32 v48, v48, v49
	v_cvt_pk_bf16_f32 v49, v50, v51
	v_cvt_pk_bf16_f32 v50, v44, v45
	v_cvt_pk_bf16_f32 v51, v46, v47
	global_store_dwordx4 v[208:209], v[48:51], off
	v_pk_fma_f32 v[40:41], v[40:41], s[48:49], v[68:69] op_sel_hi:[1,0,1]
	v_pk_fma_f32 v[42:43], v[42:43], s[48:49], v[70:71] op_sel_hi:[1,0,1]
	v_pk_fma_f32 v[36:37], v[36:37], s[48:49], v[60:61] op_sel_hi:[1,0,1]
	v_pk_fma_f32 v[38:39], v[38:39], s[48:49], v[62:63] op_sel_hi:[1,0,1]
	v_cvt_pk_bf16_f32 v40, v40, v41
	v_cvt_pk_bf16_f32 v41, v42, v43
	v_cvt_pk_bf16_f32 v42, v36, v37
	v_cvt_pk_bf16_f32 v43, v38, v39
	global_store_dwordx4 v[208:209], v[40:43], off offset:256
	s_add_u32 s44, s44, s58
	v_lshl_add_u64 v[208:209], v[206:207], 0, s[44:45]
	v_pk_fma_f32 v[32:33], v[32:33], s[48:49], v[80:81] op_sel_hi:[1,0,1]
	v_pk_fma_f32 v[34:35], v[34:35], s[48:49], v[82:83] op_sel_hi:[1,0,1]
	v_pk_fma_f32 v[28:29], v[28:29], s[48:49], v[76:77] op_sel_hi:[1,0,1]
	v_pk_fma_f32 v[30:31], v[30:31], s[48:49], v[78:79] op_sel_hi:[1,0,1]
	v_cvt_pk_bf16_f32 v32, v32, v33
	v_cvt_pk_bf16_f32 v33, v34, v35
	v_cvt_pk_bf16_f32 v34, v28, v29
	v_cvt_pk_bf16_f32 v35, v30, v31
	global_store_dwordx4 v[208:209], v[32:35], off
	v_pk_fma_f32 v[24:25], v[24:25], s[48:49], v[68:69] op_sel_hi:[1,0,1]
	v_pk_fma_f32 v[26:27], v[26:27], s[48:49], v[70:71] op_sel_hi:[1,0,1]
	v_pk_fma_f32 v[20:21], v[20:21], s[48:49], v[60:61] op_sel_hi:[1,0,1]
	v_pk_fma_f32 v[22:23], v[22:23], s[48:49], v[62:63] op_sel_hi:[1,0,1]
	v_cvt_pk_bf16_f32 v24, v24, v25
	v_cvt_pk_bf16_f32 v25, v26, v27
	v_cvt_pk_bf16_f32 v26, v20, v21
	v_cvt_pk_bf16_f32 v27, v22, v23
	global_store_dwordx4 v[208:209], v[24:27], off offset:256
	s_add_u32 s44, s44, s58
	v_lshl_add_u64 v[208:209], v[206:207], 0, s[44:45]
	v_pk_fma_f32 v[16:17], v[16:17], s[48:49], v[80:81] op_sel_hi:[1,0,1]
	v_pk_fma_f32 v[18:19], v[18:19], s[48:49], v[82:83] op_sel_hi:[1,0,1]
	v_pk_fma_f32 v[12:13], v[12:13], s[48:49], v[76:77] op_sel_hi:[1,0,1]
	v_pk_fma_f32 v[14:15], v[14:15], s[48:49], v[78:79] op_sel_hi:[1,0,1]
	v_cvt_pk_bf16_f32 v16, v16, v17
	v_cvt_pk_bf16_f32 v17, v18, v19
	v_cvt_pk_bf16_f32 v18, v12, v13
	v_cvt_pk_bf16_f32 v19, v14, v15
	global_store_dwordx4 v[208:209], v[16:19], off
	v_pk_fma_f32 v[8:9], v[8:9], s[48:49], v[68:69] op_sel_hi:[1,0,1]
	v_pk_fma_f32 v[10:11], v[10:11], s[48:49], v[70:71] op_sel_hi:[1,0,1]
	v_pk_fma_f32 v[4:5], v[4:5], s[48:49], v[60:61] op_sel_hi:[1,0,1]
	v_pk_fma_f32 v[6:7], v[6:7], s[48:49], v[62:63] op_sel_hi:[1,0,1]
	v_cvt_pk_bf16_f32 v8, v8, v9
	v_cvt_pk_bf16_f32 v9, v10, v11
	v_cvt_pk_bf16_f32 v10, v4, v5
	v_cvt_pk_bf16_f32 v11, v6, v7
	global_store_dwordx4 v[208:209], v[8:11], off offset:256
	s_branch .Lepiin_join
.Lepiin_act:
	v_pk_fma_f32 v[140:141], v[140:141], s[48:49], v[80:81] op_sel_hi:[1,0,1]
	v_pk_fma_f32 v[142:143], v[142:143], s[48:49], v[82:83] op_sel_hi:[1,0,1]
	v_pk_fma_f32 v[144:145], v[144:145], s[48:49], v[76:77] op_sel_hi:[1,0,1]
	v_pk_fma_f32 v[146:147], v[146:147], s[48:49], v[78:79] op_sel_hi:[1,0,1]
	v_exp_f32_e32 v140, v140
	v_exp_f32_e32 v141, v141
	v_exp_f32_e32 v142, v142
	v_exp_f32_e32 v143, v143
	v_exp_f32_e32 v144, v144
	v_exp_f32_e32 v145, v145
	v_exp_f32_e32 v146, v146
	v_exp_f32_e32 v147, v147
	v_add_f32_e32 v140, 1.0, v140
	v_add_f32_e32 v141, 1.0, v141
	v_add_f32_e32 v142, 1.0, v142
	v_add_f32_e32 v143, 1.0, v143
	v_add_f32_e32 v144, 1.0, v144
	v_add_f32_e32 v145, 1.0, v145
	v_add_f32_e32 v146, 1.0, v146
	v_add_f32_e32 v147, 1.0, v147
	v_rcp_f32_e32 v140, v140
	v_rcp_f32_e32 v141, v141
	v_rcp_f32_e32 v142, v142
	v_rcp_f32_e32 v143, v143
	v_rcp_f32_e32 v144, v144
	v_rcp_f32_e32 v145, v145
	v_rcp_f32_e32 v146, v146
	v_rcp_f32_e32 v147, v147
	v_cvt_pk_bf16_f32 v140, v140, v141
	v_cvt_pk_bf16_f32 v141, v142, v143
	v_cvt_pk_bf16_f32 v142, v144, v145
	v_cvt_pk_bf16_f32 v143, v146, v147
	global_store_dwordx4 v[206:207], v[140:143], off
	v_pk_fma_f32 v[136:137], v[136:137], s[48:49], v[68:69] op_sel_hi:[1,0,1]
	v_pk_fma_f32 v[138:139], v[138:139], s[48:49], v[70:71] op_sel_hi:[1,0,1]
	v_pk_fma_f32 v[132:133], v[132:133], s[48:49], v[60:61] op_sel_hi:[1,0,1]
	v_pk_fma_f32 v[134:135], v[134:135], s[48:49], v[62:63] op_sel_hi:[1,0,1]
	v_exp_f32_e32 v136, v136
	v_exp_f32_e32 v137, v137
	v_exp_f32_e32 v138, v138
	v_exp_f32_e32 v139, v139
	v_exp_f32_e32 v132, v132
	v_exp_f32_e32 v133, v133
	v_exp_f32_e32 v134, v134
	v_exp_f32_e32 v135, v135
	v_add_f32_e32 v136, 1.0, v136
	v_add_f32_e32 v137, 1.0, v137
	v_add_f32_e32 v138, 1.0, v138
	v_add_f32_e32 v139, 1.0, v139
; __device__ __forceinline__ unsigned pk2(float lo, float hi) { unsigned r; asm volatile("v_cvt_pk_bf16_f32 %0, %1, %2" : "=v"(r) : "v"(lo), "v"(hi)); return r; }
; __device__ __forceinline__ float sigmoid_fast(float x) { return __builtin_amdgcn_rcpf(1.0f + __expf(-x)); }
;     __device__ __forceinline__ void operator()(const f32x4 (&acc)[2][2][4][2], const Unit& u, int wr, int wc, int fr, int fq) const {
;     ...
;         const int cl = wc * 32 + 8 * fq;
;         const int bcol0 = pn * 256 + cl + (pn < 12 ? 0 : 8);
;         f32x4 bv[2][2];
; #pragma unroll
;         for (int bj = 0; bj < 2; ++bj)
; #pragma unroll
;             for (int n = 0; n < 2; ++n) bv[bj][n] = *(const f32x4*)(bias + bcol0 + bj * 128 + 4 * n);
; #pragma unroll
;         for (int ai = 0; ai < 2; ++ai)
; #pragma unroll
;             for (int m = 0; m < 4; ++m) {
;                 const int rloc = ai * 128 + wr * 64 + m * 16 + fr; const size_t row = (size_t)u.pm * 256 + rloc;
;                 bf16* rowp = base + row * ld + ct + cl;
;                 float* sp = nullptr;
;                 if (st) {
;                     if (u.pm >= 64) { const int rs = (u.pm - 64) * 256 + rloc; sp = so_s + ((size_t)(rs >> 2) * 128 + 124 + (rs & 3)) * 256 + cl; }
;                     else if ((u.pm & 7) == 7 && ai == 1) { sp = so_p + ((size_t)(u.pm >> 3) * 128 + (rloc - 128)) * 256 + cl; }
;                 }
; #pragma unroll
;                 for (int bj = 0; bj < 2; ++bj) {
;                     f32x4 v0 = (acc[ai][bj][m][0] + bv[bj][0]) * sc, v1 = (acc[ai][bj][m][1] + bv[bj][1]) * sc;
;                     if (act) {
; #pragma unroll
;                         for (int j = 0; j < 4; ++j) { v0[j] = sigmoid_fast(v0[j]); v1[j] = sigmoid_fast(v1[j]); }
;                     }
;                     u32x4 w; w.x = pk2(v0[0], v0[1]); w.y = pk2(v0[2], v0[3]); w.z = pk2(v1[0], v1[1]); w.w = pk2(v1[2], v1[3]);
;                     if (act) __builtin_nontemporal_store(w, (u32x4*)(rowp + bj * 128)); else *(u32x4*)(rowp + bj * 128) = w;
;                     if (sp) { *(f32x4*)(sp + bj * 128) = v0; *(f32x4*)(sp + bj * 128 + 4) = v1; }
;                 }
	v_add_f32_e32 v132, 1.0, v132
	v_add_f32_e32 v133, 1.0, v133
	v_add_f32_e32 v134, 1.0, v134
	v_add_f32_e32 v135, 1.0, v135
	v_rcp_f32_e32 v136, v136
	v_rcp_f32_e32 v137, v137
	v_rcp_f32_e32 v138, v138
	v_rcp_f32_e32 v139, v139
	v_rcp_f32_e32 v132, v132
	v_rcp_f32_e32 v133, v133
	v_rcp_f32_e32 v134, v134
	v_rcp_f32_e32 v135, v135
	v_cvt_pk_bf16_f32 v136, v136, v137
	v_cvt_pk_bf16_f32 v137, v138, v139
	v_cvt_pk_bf16_f32 v138, v132, v133
	v_cvt_pk_bf16_f32 v139, v134, v135
	global_store_dwordx4 v[206:207], v[136:139], off offset:256
	s_add_u32 s44, s44, s58
	v_lshl_add_u64 v[208:209], v[206:207], 0, s[44:45]
	v_pk_fma_f32 v[128:129], v[128:129], s[48:49], v[80:81] op_sel_hi:[1,0,1]
	v_pk_fma_f32 v[130:131], v[130:131], s[48:49], v[82:83] op_sel_hi:[1,0,1]
	v_pk_fma_f32 v[124:125], v[124:125], s[48:49], v[76:77] op_sel_hi:[1,0,1]
	v_pk_fma_f32 v[126:127], v[126:127], s[48:49], v[78:79] op_sel_hi:[1,0,1]
	v_exp_f32_e32 v128, v128
	v_exp_f32_e32 v129, v129
	v_exp_f32_e32 v130, v130
	v_exp_f32_e32 v131, v131
	v_exp_f32_e32 v124, v124
	v_exp_f32_e32 v125, v125
	v_exp_f32_e32 v126, v126
	v_exp_f32_e32 v127, v127
	v_add_f32_e32 v128, 1.0, v128
	v_add_f32_e32 v129, 1.0, v129
	v_add_f32_e32 v130, 1.0, v130
	v_add_f32_e32 v131, 1.0, v131
	v_add_f32_e32 v124, 1.0, v124
	v_add_f32_e32 v125, 1.0, v125
	v_add_f32_e32 v126, 1.0, v126
	v_add_f32_e32 v127, 1.0, v127
	v_rcp_f32_e32 v128, v128
	v_rcp_f32_e32 v129, v129
	v_rcp_f32_e32 v130, v130
	v_rcp_f32_e32 v131, v131
	v_rcp_f32_e32 v124, v124
	v_rcp_f32_e32 v125, v125
	v_rcp_f32_e32 v126, v126
	v_rcp_f32_e32 v127, v127
	v_cvt_pk_bf16_f32 v128, v128, v129
	v_cvt_pk_bf16_f32 v129, v130, v131
	v_cvt_pk_bf16_f32 v130, v124, v125
	v_cvt_pk_bf16_f32 v131, v126, v127
	global_store_dwordx4 v[208:209], v[128:131], off
	v_pk_fma_f32 v[120:121], v[120:121], s[48:49], v[68:69] op_sel_hi:[1,0,1]
	v_pk_fma_f32 v[122:123], v[122:123], s[48:49], v[70:71] op_sel_hi:[1,0,1]
	v_pk_fma_f32 v[116:117], v[116:117], s[48:49], v[60:61] op_sel_hi:[1,0,1]
	v_pk_fma_f32 v[118:119], v[118:119], s[48:49], v[62:63] op_sel_hi:[1,0,1]
	v_exp_f32_e32 v120, v120
	v_exp_f32_e32 v121, v121
	v_exp_f32_e32 v122, v122
	v_exp_f32_e32 v123, v123
	v_exp_f32_e32 v116, v116
	v_exp_f32_e32 v117, v117
	v_exp_f32_e32 v118, v118
	v_exp_f32_e32 v119, v119
	v_add_f32_e32 v120, 1.0, v120
	v_add_f32_e32 v121, 1.0, v121
	v_add_f32_e32 v122, 1.0, v122
	v_add_f32_e32 v123, 1.0, v123
	v_add_f32_e32 v116, 1.0, v116
	v_add_f32_e32 v117, 1.0, v117
	v_add_f32_e32 v118, 1.0, v118
	v_add_f32_e32 v119, 1.0, v119
	v_rcp_f32_e32 v120, v120
	v_rcp_f32_e32 v121, v121
	v_rcp_f32_e32 v122, v122
	v_rcp_f32_e32 v123, v123
	v_rcp_f32_e32 v116, v116
	v_rcp_f32_e32 v117, v117
	v_rcp_f32_e32 v118, v118
	v_rcp_f32_e32 v119, v119
	v_cvt_pk_bf16_f32 v120, v120, v121
	v_cvt_pk_bf16_f32 v121, v122, v123
	v_cvt_pk_bf16_f32 v122, v116, v117
	v_cvt_pk_bf16_f32 v123, v118, v119
	global_store_dwordx4 v[208:209], v[120:123], off offset:256
	s_add_u32 s44, s44, s58
	v_lshl_add_u64 v[208:209], v[206:207], 0, s[44:45]
	v_pk_fma_f32 v[112:113], v[112:113], s[48:49], v[80:81] op_sel_hi:[1,0,1]
	v_pk_fma_f32 v[114:115], v[114:115], s[48:49], v[82:83] op_sel_hi:[1,0,1]
	v_pk_fma_f32 v[108:109], v[108:109], s[48:49], v[76:77] op_sel_hi:[1,0,1]
	v_pk_fma_f32 v[110:111], v[110:111], s[48:49], v[78:79] op_sel_hi:[1,0,1]
	v_exp_f32_e32 v112, v112
	v_exp_f32_e32 v113, v113
	v_exp_f32_e32 v114, v114
	v_exp_f32_e32 v115, v115
	v_exp_f32_e32 v108, v108
	v_exp_f32_e32 v109, v109
	v_exp_f32_e32 v110, v110
	v_exp_f32_e32 v111, v111
	v_add_f32_e32 v112, 1.0, v112
	v_add_f32_e32 v113, 1.0, v113
	v_add_f32_e32 v114, 1.0, v114
	v_add_f32_e32 v115, 1.0, v115
	v_add_f32_e32 v108, 1.0, v108
	v_add_f32_e32 v109, 1.0, v109
	v_add_f32_e32 v110, 1.0, v110
	v_add_f32_e32 v111, 1.0, v111
	v_rcp_f32_e32 v112, v112
	v_rcp_f32_e32 v113, v113
	v_rcp_f32_e32 v114, v114
	v_rcp_f32_e32 v115, v115
	v_rcp_f32_e32 v108, v108
	v_rcp_f32_e32 v109, v109
	v_rcp_f32_e32 v110, v110
	v_rcp_f32_e32 v111, v111
	v_cvt_pk_bf16_f32 v112, v112, v113
	v_cvt_pk_bf16_f32 v113, v114, v115
	v_cvt_pk_bf16_f32 v114, v108, v109
	v_cvt_pk_bf16_f32 v115, v110, v111
	global_store_dwordx4 v[208:209], v[112:115], off
	v_pk_fma_f32 v[104:105], v[104:105], s[48:49], v[68:69] op_sel_hi:[1,0,1]
	v_pk_fma_f32 v[106:107], v[106:107], s[48:49], v[70:71] op_sel_hi:[1,0,1]
	v_pk_fma_f32 v[100:101], v[100:101], s[48:49], v[60:61] op_sel_hi:[1,0,1]
	v_pk_fma_f32 v[102:103], v[102:103], s[48:49], v[62:63] op_sel_hi:[1,0,1]
	v_exp_f32_e32 v104, v104
	v_exp_f32_e32 v105, v105
	v_exp_f32_e32 v106, v106
	v_exp_f32_e32 v107, v107
	v_exp_f32_e32 v100, v100
	v_exp_f32_e32 v101, v101
	v_exp_f32_e32 v102, v102
	v_exp_f32_e32 v103, v103
	v_add_f32_e32 v104, 1.0, v104
	v_add_f32_e32 v105, 1.0, v105
	v_add_f32_e32 v106, 1.0, v106
	v_add_f32_e32 v107, 1.0, v107
	v_add_f32_e32 v100, 1.0, v100
	v_add_f32_e32 v101, 1.0, v101
	v_add_f32_e32 v102, 1.0, v102
	v_add_f32_e32 v103, 1.0, v103
	v_rcp_f32_e32 v104, v104
	v_rcp_f32_e32 v105, v105
	v_rcp_f32_e32 v106, v106
	v_rcp_f32_e32 v107, v107
	v_rcp_f32_e32 v100, v100
	v_rcp_f32_e32 v101, v101
	v_rcp_f32_e32 v102, v102
	v_rcp_f32_e32 v103, v103
	v_cvt_pk_bf16_f32 v104, v104, v105
	v_cvt_pk_bf16_f32 v105, v106, v107
	v_cvt_pk_bf16_f32 v106, v100, v101
	v_cvt_pk_bf16_f32 v107, v102, v103
	global_store_dwordx4 v[208:209], v[104:107], off offset:256
	s_add_u32 s44, s44, s58
	v_lshl_add_u64 v[208:209], v[206:207], 0, s[44:45]
	v_pk_fma_f32 v[96:97], v[96:97], s[48:49], v[80:81] op_sel_hi:[1,0,1]
	v_pk_fma_f32 v[98:99], v[98:99], s[48:49], v[82:83] op_sel_hi:[1,0,1]
	v_pk_fma_f32 v[92:93], v[92:93], s[48:49], v[76:77] op_sel_hi:[1,0,1]
; __device__ __forceinline__ unsigned pk2(float lo, float hi) { unsigned r; asm volatile("v_cvt_pk_bf16_f32 %0, %1, %2" : "=v"(r) : "v"(lo), "v"(hi)); return r; }
; __device__ __forceinline__ float sigmoid_fast(float x) { return __builtin_amdgcn_rcpf(1.0f + __expf(-x)); }
;     __device__ __forceinline__ void operator()(const f32x4 (&acc)[2][2][4][2], const Unit& u, int wr, int wc, int fr, int fq) const {
;     ...
;         const int cl = wc * 32 + 8 * fq;
;         const int bcol0 = pn * 256 + cl + (pn < 12 ? 0 : 8);
;         f32x4 bv[2][2];
; #pragma unroll
;         for (int bj = 0; bj < 2; ++bj)
; #pragma unroll
;             for (int n = 0; n < 2; ++n) bv[bj][n] = *(const f32x4*)(bias + bcol0 + bj * 128 + 4 * n);
; #pragma unroll
;         for (int ai = 0; ai < 2; ++ai)
; #pragma unroll
;             for (int m = 0; m < 4; ++m) {
;                 const int rloc = ai * 128 + wr * 64 + m * 16 + fr; const size_t row = (size_t)u.pm * 256 + rloc;
;                 bf16* rowp = base + row * ld + ct + cl;
;                 float* sp = nullptr;
;                 if (st) {
;                     if (u.pm >= 64) { const int rs = (u.pm - 64) * 256 + rloc; sp = so_s + ((size_t)(rs >> 2) * 128 + 124 + (rs & 3)) * 256 + cl; }
;                     else if ((u.pm & 7) == 7 && ai == 1) { sp = so_p + ((size_t)(u.pm >> 3) * 128 + (rloc - 128)) * 256 + cl; }
;                 }
; #pragma unroll
;                 for (int bj = 0; bj < 2; ++bj) {
;                     f32x4 v0 = (acc[ai][bj][m][0] + bv[bj][0]) * sc, v1 = (acc[ai][bj][m][1] + bv[bj][1]) * sc;
;                     if (act) {
; #pragma unroll
;                         for (int j = 0; j < 4; ++j) { v0[j] = sigmoid_fast(v0[j]); v1[j] = sigmoid_fast(v1[j]); }
;                     }
;                     u32x4 w; w.x = pk2(v0[0], v0[1]); w.y = pk2(v0[2], v0[3]); w.z = pk2(v1[0], v1[1]); w.w = pk2(v1[2], v1[3]);
;                     if (act) __builtin_nontemporal_store(w, (u32x4*)(rowp + bj * 128)); else *(u32x4*)(rowp + bj * 128) = w;
;                     if (sp) { *(f32x4*)(sp + bj * 128) = v0; *(f32x4*)(sp + bj * 128 + 4) = v1; }
;                 }
	v_pk_fma_f32 v[94:95], v[94:95], s[48:49], v[78:79] op_sel_hi:[1,0,1]
	v_exp_f32_e32 v96, v96
	v_exp_f32_e32 v97, v97
	v_exp_f32_e32 v98, v98
	v_exp_f32_e32 v99, v99
	v_exp_f32_e32 v92, v92
	v_exp_f32_e32 v93, v93
	v_exp_f32_e32 v94, v94
	v_exp_f32_e32 v95, v95
	v_add_f32_e32 v96, 1.0, v96
	v_add_f32_e32 v97, 1.0, v97
	v_add_f32_e32 v98, 1.0, v98
	v_add_f32_e32 v99, 1.0, v99
	v_add_f32_e32 v92, 1.0, v92
	v_add_f32_e32 v93, 1.0, v93
	v_add_f32_e32 v94, 1.0, v94
	v_add_f32_e32 v95, 1.0, v95
	v_rcp_f32_e32 v96, v96
	v_rcp_f32_e32 v97, v97
	v_rcp_f32_e32 v98, v98
	v_rcp_f32_e32 v99, v99
	v_rcp_f32_e32 v92, v92
	v_rcp_f32_e32 v93, v93
	v_rcp_f32_e32 v94, v94
	v_rcp_f32_e32 v95, v95
	v_cvt_pk_bf16_f32 v96, v96, v97
	v_cvt_pk_bf16_f32 v97, v98, v99
	v_cvt_pk_bf16_f32 v98, v92, v93
	v_cvt_pk_bf16_f32 v99, v94, v95
	global_store_dwordx4 v[208:209], v[96:99], off
	v_pk_fma_f32 v[88:89], v[88:89], s[48:49], v[68:69] op_sel_hi:[1,0,1]
	v_pk_fma_f32 v[90:91], v[90:91], s[48:49], v[70:71] op_sel_hi:[1,0,1]
	v_pk_fma_f32 v[84:85], v[84:85], s[48:49], v[60:61] op_sel_hi:[1,0,1]
	v_pk_fma_f32 v[86:87], v[86:87], s[48:49], v[62:63] op_sel_hi:[1,0,1]
	v_exp_f32_e32 v88, v88
	v_exp_f32_e32 v89, v89
	v_exp_f32_e32 v90, v90
	v_exp_f32_e32 v91, v91
	v_exp_f32_e32 v84, v84
	v_exp_f32_e32 v85, v85
	v_exp_f32_e32 v86, v86
	v_exp_f32_e32 v87, v87
	v_add_f32_e32 v88, 1.0, v88
	v_add_f32_e32 v89, 1.0, v89
	v_add_f32_e32 v90, 1.0, v90
	v_add_f32_e32 v91, 1.0, v91
	v_add_f32_e32 v84, 1.0, v84
	v_add_f32_e32 v85, 1.0, v85
	v_add_f32_e32 v86, 1.0, v86
	v_add_f32_e32 v87, 1.0, v87
	v_rcp_f32_e32 v88, v88
	v_rcp_f32_e32 v89, v89
	v_rcp_f32_e32 v90, v90
	v_rcp_f32_e32 v91, v91
	v_rcp_f32_e32 v84, v84
	v_rcp_f32_e32 v85, v85
	v_rcp_f32_e32 v86, v86
	v_rcp_f32_e32 v87, v87
	v_cvt_pk_bf16_f32 v88, v88, v89
	v_cvt_pk_bf16_f32 v89, v90, v91
	v_cvt_pk_bf16_f32 v90, v84, v85
	v_cvt_pk_bf16_f32 v91, v86, v87
	global_store_dwordx4 v[208:209], v[88:91], off offset:256
	s_mov_b32 s44, s59
	v_lshl_add_u64 v[208:209], v[206:207], 0, s[44:45]
	v_pk_fma_f32 v[72:73], v[72:73], s[48:49], v[80:81] op_sel_hi:[1,0,1]
	v_pk_fma_f32 v[74:75], v[74:75], s[48:49], v[82:83] op_sel_hi:[1,0,1]
	v_pk_fma_f32 v[64:65], v[64:65], s[48:49], v[76:77] op_sel_hi:[1,0,1]
	v_pk_fma_f32 v[66:67], v[66:67], s[48:49], v[78:79] op_sel_hi:[1,0,1]
	v_exp_f32_e32 v72, v72
	v_exp_f32_e32 v73, v73
	v_exp_f32_e32 v74, v74
	v_exp_f32_e32 v75, v75
	v_exp_f32_e32 v64, v64
	v_exp_f32_e32 v65, v65
	v_exp_f32_e32 v66, v66
	v_exp_f32_e32 v67, v67
	v_add_f32_e32 v72, 1.0, v72
	v_add_f32_e32 v73, 1.0, v73
	v_add_f32_e32 v74, 1.0, v74
	v_add_f32_e32 v75, 1.0, v75
	v_add_f32_e32 v64, 1.0, v64
	v_add_f32_e32 v65, 1.0, v65
	v_add_f32_e32 v66, 1.0, v66
	v_add_f32_e32 v67, 1.0, v67
	v_rcp_f32_e32 v72, v72
	v_rcp_f32_e32 v73, v73
	v_rcp_f32_e32 v74, v74
	v_rcp_f32_e32 v75, v75
	v_rcp_f32_e32 v64, v64
	v_rcp_f32_e32 v65, v65
	v_rcp_f32_e32 v66, v66
	v_rcp_f32_e32 v67, v67
	v_cvt_pk_bf16_f32 v72, v72, v73
	v_cvt_pk_bf16_f32 v73, v74, v75
	v_cvt_pk_bf16_f32 v74, v64, v65
	v_cvt_pk_bf16_f32 v75, v66, v67
	global_store_dwordx4 v[208:209], v[72:75], off
	v_pk_fma_f32 v[56:57], v[56:57], s[48:49], v[68:69] op_sel_hi:[1,0,1]
	v_pk_fma_f32 v[58:59], v[58:59], s[48:49], v[70:71] op_sel_hi:[1,0,1]
	v_pk_fma_f32 v[52:53], v[52:53], s[48:49], v[60:61] op_sel_hi:[1,0,1]
	v_pk_fma_f32 v[54:55], v[54:55], s[48:49], v[62:63] op_sel_hi:[1,0,1]
	v_exp_f32_e32 v56, v56
	v_exp_f32_e32 v57, v57
	v_exp_f32_e32 v58, v58
	v_exp_f32_e32 v59, v59
	v_exp_f32_e32 v52, v52
	v_exp_f32_e32 v53, v53
	v_exp_f32_e32 v54, v54
	v_exp_f32_e32 v55, v55
	v_add_f32_e32 v56, 1.0, v56
	v_add_f32_e32 v57, 1.0, v57
	v_add_f32_e32 v58, 1.0, v58
	v_add_f32_e32 v59, 1.0, v59
	v_add_f32_e32 v52, 1.0, v52
	v_add_f32_e32 v53, 1.0, v53
	v_add_f32_e32 v54, 1.0, v54
	v_add_f32_e32 v55, 1.0, v55
	v_rcp_f32_e32 v56, v56
	v_rcp_f32_e32 v57, v57
	v_rcp_f32_e32 v58, v58
	v_rcp_f32_e32 v59, v59
	v_rcp_f32_e32 v52, v52
	v_rcp_f32_e32 v53, v53
	v_rcp_f32_e32 v54, v54
	v_rcp_f32_e32 v55, v55
	v_cvt_pk_bf16_f32 v56, v56, v57
	v_cvt_pk_bf16_f32 v57, v58, v59
	v_cvt_pk_bf16_f32 v58, v52, v53
	v_cvt_pk_bf16_f32 v59, v54, v55
	global_store_dwordx4 v[208:209], v[56:59], off offset:256
	s_add_u32 s44, s44, s58
	v_lshl_add_u64 v[208:209], v[206:207], 0, s[44:45]
	v_pk_fma_f32 v[48:49], v[48:49], s[48:49], v[80:81] op_sel_hi:[1,0,1]
	v_pk_fma_f32 v[50:51], v[50:51], s[48:49], v[82:83] op_sel_hi:[1,0,1]
	v_pk_fma_f32 v[44:45], v[44:45], s[48:49], v[76:77] op_sel_hi:[1,0,1]
	v_pk_fma_f32 v[46:47], v[46:47], s[48:49], v[78:79] op_sel_hi:[1,0,1]
	v_exp_f32_e32 v48, v48
	v_exp_f32_e32 v49, v49
	v_exp_f32_e32 v50, v50
	v_exp_f32_e32 v51, v51
	v_exp_f32_e32 v44, v44
	v_exp_f32_e32 v45, v45
	v_exp_f32_e32 v46, v46
	v_exp_f32_e32 v47, v47
	v_add_f32_e32 v48, 1.0, v48
	v_add_f32_e32 v49, 1.0, v49
	v_add_f32_e32 v50, 1.0, v50
	v_add_f32_e32 v51, 1.0, v51
	v_add_f32_e32 v44, 1.0, v44
	v_add_f32_e32 v45, 1.0, v45
	v_add_f32_e32 v46, 1.0, v46
	v_add_f32_e32 v47, 1.0, v47
	v_rcp_f32_e32 v48, v48
	v_rcp_f32_e32 v49, v49
	v_rcp_f32_e32 v50, v50
	v_rcp_f32_e32 v51, v51
	v_rcp_f32_e32 v44, v44
	v_rcp_f32_e32 v45, v45
	v_rcp_f32_e32 v46, v46
	v_rcp_f32_e32 v47, v47
	v_cvt_pk_bf16_f32 v48, v48, v49
	v_cvt_pk_bf16_f32 v49, v50, v51
	v_cvt_pk_bf16_f32 v50, v44, v45
	v_cvt_pk_bf16_f32 v51, v46, v47
	global_store_dwordx4 v[208:209], v[48:51], off
	v_pk_fma_f32 v[40:41], v[40:41], s[48:49], v[68:69] op_sel_hi:[1,0,1]
; __device__ __forceinline__ unsigned pk2(float lo, float hi) { unsigned r; asm volatile("v_cvt_pk_bf16_f32 %0, %1, %2" : "=v"(r) : "v"(lo), "v"(hi)); return r; }
; __device__ __forceinline__ float sigmoid_fast(float x) { return __builtin_amdgcn_rcpf(1.0f + __expf(-x)); }
;     __device__ __forceinline__ void operator()(const f32x4 (&acc)[2][2][4][2], const Unit& u, int wr, int wc, int fr, int fq) const {
;     ...
;         const int cl = wc * 32 + 8 * fq;
;         const int bcol0 = pn * 256 + cl + (pn < 12 ? 0 : 8);
;         f32x4 bv[2][2];
; #pragma unroll
;         for (int bj = 0; bj < 2; ++bj)
; #pragma unroll
;             for (int n = 0; n < 2; ++n) bv[bj][n] = *(const f32x4*)(bias + bcol0 + bj * 128 + 4 * n);
; #pragma unroll
;         for (int ai = 0; ai < 2; ++ai)
; #pragma unroll
;             for (int m = 0; m < 4; ++m) {
;                 const int rloc = ai * 128 + wr * 64 + m * 16 + fr; const size_t row = (size_t)u.pm * 256 + rloc;
;                 bf16* rowp = base + row * ld + ct + cl;
;                 float* sp = nullptr;
;                 if (st) {
;                     if (u.pm >= 64) { const int rs = (u.pm - 64) * 256 + rloc; sp = so_s + ((size_t)(rs >> 2) * 128 + 124 + (rs & 3)) * 256 + cl; }
;                     else if ((u.pm & 7) == 7 && ai == 1) { sp = so_p + ((size_t)(u.pm >> 3) * 128 + (rloc - 128)) * 256 + cl; }
;                 }
; #pragma unroll
;                 for (int bj = 0; bj < 2; ++bj) {
;                     f32x4 v0 = (acc[ai][bj][m][0] + bv[bj][0]) * sc, v1 = (acc[ai][bj][m][1] + bv[bj][1]) * sc;
;                     if (act) {
; #pragma unroll
;                         for (int j = 0; j < 4; ++j) { v0[j] = sigmoid_fast(v0[j]); v1[j] = sigmoid_fast(v1[j]); }
;                     }
;                     u32x4 w; w.x = pk2(v0[0], v0[1]); w.y = pk2(v0[2], v0[3]); w.z = pk2(v1[0], v1[1]); w.w = pk2(v1[2], v1[3]);
;                     if (act) __builtin_nontemporal_store(w, (u32x4*)(rowp + bj * 128)); else *(u32x4*)(rowp + bj * 128) = w;
;                     if (sp) { *(f32x4*)(sp + bj * 128) = v0; *(f32x4*)(sp + bj * 128 + 4) = v1; }
;                 }
	v_pk_fma_f32 v[42:43], v[42:43], s[48:49], v[70:71] op_sel_hi:[1,0,1]
	v_pk_fma_f32 v[36:37], v[36:37], s[48:49], v[60:61] op_sel_hi:[1,0,1]
	v_pk_fma_f32 v[38:39], v[38:39], s[48:49], v[62:63] op_sel_hi:[1,0,1]
	v_exp_f32_e32 v40, v40
	v_exp_f32_e32 v41, v41
	v_exp_f32_e32 v42, v42
	v_exp_f32_e32 v43, v43
	v_exp_f32_e32 v36, v36
	v_exp_f32_e32 v37, v37
	v_exp_f32_e32 v38, v38
	v_exp_f32_e32 v39, v39
	v_add_f32_e32 v40, 1.0, v40
	v_add_f32_e32 v41, 1.0, v41
	v_add_f32_e32 v42, 1.0, v42
	v_add_f32_e32 v43, 1.0, v43
	v_add_f32_e32 v36, 1.0, v36
	v_add_f32_e32 v37, 1.0, v37
	v_add_f32_e32 v38, 1.0, v38
	v_add_f32_e32 v39, 1.0, v39
	v_rcp_f32_e32 v40, v40
	v_rcp_f32_e32 v41, v41
	v_rcp_f32_e32 v42, v42
	v_rcp_f32_e32 v43, v43
	v_rcp_f32_e32 v36, v36
	v_rcp_f32_e32 v37, v37
	v_rcp_f32_e32 v38, v38
	v_rcp_f32_e32 v39, v39
	v_cvt_pk_bf16_f32 v40, v40, v41
	v_cvt_pk_bf16_f32 v41, v42, v43
	v_cvt_pk_bf16_f32 v42, v36, v37
	v_cvt_pk_bf16_f32 v43, v38, v39
	global_store_dwordx4 v[208:209], v[40:43], off offset:256
	s_add_u32 s44, s44, s58
	v_lshl_add_u64 v[208:209], v[206:207], 0, s[44:45]
	v_pk_fma_f32 v[32:33], v[32:33], s[48:49], v[80:81] op_sel_hi:[1,0,1]
	v_pk_fma_f32 v[34:35], v[34:35], s[48:49], v[82:83] op_sel_hi:[1,0,1]
	v_pk_fma_f32 v[28:29], v[28:29], s[48:49], v[76:77] op_sel_hi:[1,0,1]
	v_pk_fma_f32 v[30:31], v[30:31], s[48:49], v[78:79] op_sel_hi:[1,0,1]
	v_exp_f32_e32 v32, v32
	v_exp_f32_e32 v33, v33
	v_exp_f32_e32 v34, v34
	v_exp_f32_e32 v35, v35
	v_exp_f32_e32 v28, v28
	v_exp_f32_e32 v29, v29
	v_exp_f32_e32 v30, v30
	v_exp_f32_e32 v31, v31
	v_add_f32_e32 v32, 1.0, v32
	v_add_f32_e32 v33, 1.0, v33
	v_add_f32_e32 v34, 1.0, v34
	v_add_f32_e32 v35, 1.0, v35
	v_add_f32_e32 v28, 1.0, v28
	v_add_f32_e32 v29, 1.0, v29
	v_add_f32_e32 v30, 1.0, v30
	v_add_f32_e32 v31, 1.0, v31
	v_rcp_f32_e32 v32, v32
	v_rcp_f32_e32 v33, v33
	v_rcp_f32_e32 v34, v34
	v_rcp_f32_e32 v35, v35
	v_rcp_f32_e32 v28, v28
	v_rcp_f32_e32 v29, v29
	v_rcp_f32_e32 v30, v30
	v_rcp_f32_e32 v31, v31
	v_cvt_pk_bf16_f32 v32, v32, v33
	v_cvt_pk_bf16_f32 v33, v34, v35
	v_cvt_pk_bf16_f32 v34, v28, v29
	v_cvt_pk_bf16_f32 v35, v30, v31
	global_store_dwordx4 v[208:209], v[32:35], off
	v_pk_fma_f32 v[24:25], v[24:25], s[48:49], v[68:69] op_sel_hi:[1,0,1]
	v_pk_fma_f32 v[26:27], v[26:27], s[48:49], v[70:71] op_sel_hi:[1,0,1]
	v_pk_fma_f32 v[20:21], v[20:21], s[48:49], v[60:61] op_sel_hi:[1,0,1]
	v_pk_fma_f32 v[22:23], v[22:23], s[48:49], v[62:63] op_sel_hi:[1,0,1]
	v_exp_f32_e32 v24, v24
	v_exp_f32_e32 v25, v25
	v_exp_f32_e32 v26, v26
	v_exp_f32_e32 v27, v27
	v_exp_f32_e32 v20, v20
	v_exp_f32_e32 v21, v21
	v_exp_f32_e32 v22, v22
	v_exp_f32_e32 v23, v23
	v_add_f32_e32 v24, 1.0, v24
	v_add_f32_e32 v25, 1.0, v25
	v_add_f32_e32 v26, 1.0, v26
	v_add_f32_e32 v27, 1.0, v27
	v_add_f32_e32 v20, 1.0, v20
	v_add_f32_e32 v21, 1.0, v21
	v_add_f32_e32 v22, 1.0, v22
	v_add_f32_e32 v23, 1.0, v23
	v_rcp_f32_e32 v24, v24
	v_rcp_f32_e32 v25, v25
	v_rcp_f32_e32 v26, v26
	v_rcp_f32_e32 v27, v27
	v_rcp_f32_e32 v20, v20
	v_rcp_f32_e32 v21, v21
	v_rcp_f32_e32 v22, v22
	v_rcp_f32_e32 v23, v23
	v_cvt_pk_bf16_f32 v24, v24, v25
	v_cvt_pk_bf16_f32 v25, v26, v27
	v_cvt_pk_bf16_f32 v26, v20, v21
	v_cvt_pk_bf16_f32 v27, v22, v23
	global_store_dwordx4 v[208:209], v[24:27], off offset:256
	s_add_u32 s44, s44, s58
	v_lshl_add_u64 v[208:209], v[206:207], 0, s[44:45]
	v_pk_fma_f32 v[16:17], v[16:17], s[48:49], v[80:81] op_sel_hi:[1,0,1]
	v_pk_fma_f32 v[18:19], v[18:19], s[48:49], v[82:83] op_sel_hi:[1,0,1]
	v_pk_fma_f32 v[12:13], v[12:13], s[48:49], v[76:77] op_sel_hi:[1,0,1]
	v_pk_fma_f32 v[14:15], v[14:15], s[48:49], v[78:79] op_sel_hi:[1,0,1]
	v_exp_f32_e32 v16, v16
	v_exp_f32_e32 v17, v17
	v_exp_f32_e32 v18, v18
	v_exp_f32_e32 v19, v19
	v_exp_f32_e32 v12, v12
	v_exp_f32_e32 v13, v13
	v_exp_f32_e32 v14, v14
	v_exp_f32_e32 v15, v15
	v_add_f32_e32 v16, 1.0, v16
	v_add_f32_e32 v17, 1.0, v17
	v_add_f32_e32 v18, 1.0, v18
	v_add_f32_e32 v19, 1.0, v19
	v_add_f32_e32 v12, 1.0, v12
	v_add_f32_e32 v13, 1.0, v13
	v_add_f32_e32 v14, 1.0, v14
	v_add_f32_e32 v15, 1.0, v15
	v_rcp_f32_e32 v16, v16
	v_rcp_f32_e32 v17, v17
	v_rcp_f32_e32 v18, v18
	v_rcp_f32_e32 v19, v19
	v_rcp_f32_e32 v12, v12
	v_rcp_f32_e32 v13, v13
	v_rcp_f32_e32 v14, v14
	v_rcp_f32_e32 v15, v15
	v_cvt_pk_bf16_f32 v16, v16, v17
	v_cvt_pk_bf16_f32 v17, v18, v19
	v_cvt_pk_bf16_f32 v18, v12, v13
	v_cvt_pk_bf16_f32 v19, v14, v15
	global_store_dwordx4 v[208:209], v[16:19], off
	v_pk_fma_f32 v[8:9], v[8:9], s[48:49], v[68:69] op_sel_hi:[1,0,1]
	v_pk_fma_f32 v[10:11], v[10:11], s[48:49], v[70:71] op_sel_hi:[1,0,1]
	v_pk_fma_f32 v[4:5], v[4:5], s[48:49], v[60:61] op_sel_hi:[1,0,1]
	v_pk_fma_f32 v[6:7], v[6:7], s[48:49], v[62:63] op_sel_hi:[1,0,1]
	v_exp_f32_e32 v8, v8
	v_exp_f32_e32 v9, v9
	v_exp_f32_e32 v10, v10
	v_exp_f32_e32 v11, v11
	v_exp_f32_e32 v4, v4
	v_exp_f32_e32 v5, v5
	v_exp_f32_e32 v6, v6
	v_exp_f32_e32 v7, v7
	v_add_f32_e32 v8, 1.0, v8
	v_add_f32_e32 v9, 1.0, v9
	v_add_f32_e32 v10, 1.0, v10
	v_add_f32_e32 v11, 1.0, v11
	v_add_f32_e32 v4, 1.0, v4
	v_add_f32_e32 v5, 1.0, v5
	v_add_f32_e32 v6, 1.0, v6
	v_add_f32_e32 v7, 1.0, v7
	v_rcp_f32_e32 v8, v8
	v_rcp_f32_e32 v9, v9
	v_rcp_f32_e32 v10, v10
	v_rcp_f32_e32 v11, v11
	v_rcp_f32_e32 v4, v4
	v_rcp_f32_e32 v5, v5
	v_rcp_f32_e32 v6, v6
	v_rcp_f32_e32 v7, v7
	v_cvt_pk_bf16_f32 v8, v8, v9
	v_cvt_pk_bf16_f32 v9, v10, v11
	v_cvt_pk_bf16_f32 v10, v4, v5
	v_cvt_pk_bf16_f32 v11, v6, v7
	global_store_dwordx4 v[208:209], v[8:11], off offset:256
	s_branch .Lepiin_join
